# G6 GEMM switched to v_mfma_f32_16x16x32_bf16 (same bf16 operands, f32 accumulate) with matching resid epilogue mapping
# baseline (speedup 1.0000x reference)
.LBB0_224:
	s_or_b64 exec, exec, s[0:1]
	v_lshrrev_b32_e32 v229, 8, v224
	v_bfe_u32 v230, v224, 4, 2
	v_lshlrev_b32_e32 v229, 7, v229
	v_lshl_add_u32 v229, v230, 2, v229
	v_add_u32_e32 v229, v170, v229
	v_lshlrev_b32_e32 v233, 12, v229
	v_and_b32_e32 v229, 0xcf, v224
	v_or_b32_e32 v229, v169, v229
	v_lshl_add_u32 v233, v229, 2, v233
	s_mov_b32 s0, s68
	s_mov_b32 s1, s69
	global_load_dword v131, v233, s[0:1]
	global_load_dword v136, v233, s[0:1] offset:64
	global_load_dword v140, v233, s[0:1] offset:128
	global_load_dword v144, v233, s[0:1] offset:192
	s_add_u32 s0, s68, 0x1000
	s_addc_u32 s1, s69, 0
	global_load_dword v132, v233, s[0:1]
	global_load_dword v137, v233, s[0:1] offset:64
	global_load_dword v141, v233, s[0:1] offset:128
	global_load_dword v145, v233, s[0:1] offset:192
	s_add_u32 s0, s68, 0x2000
	s_addc_u32 s1, s69, 0
	global_load_dword v134, v233, s[0:1]
	global_load_dword v138, v233, s[0:1] offset:64
	global_load_dword v142, v233, s[0:1] offset:128
	global_load_dword v149, v233, s[0:1] offset:192
	s_add_u32 s0, s68, 0x3000
	s_addc_u32 s1, s69, 0
	global_load_dword v135, v233, s[0:1]
	global_load_dword v139, v233, s[0:1] offset:64
	global_load_dword v143, v233, s[0:1] offset:128
	global_load_dword v150, v233, s[0:1] offset:192
	s_add_u32 s0, s68, 0x10000
	s_addc_u32 s1, s69, 0
	global_load_dword v151, v233, s[0:1]
	global_load_dword v155, v233, s[0:1] offset:64
	global_load_dword v159, v233, s[0:1] offset:128
	global_load_dword v163, v233, s[0:1] offset:192
	s_add_u32 s0, s68, 0x11000
	s_addc_u32 s1, s69, 0
	global_load_dword v152, v233, s[0:1]
	global_load_dword v156, v233, s[0:1] offset:64
	global_load_dword v160, v233, s[0:1] offset:128
	global_load_dword v164, v233, s[0:1] offset:192
	s_add_u32 s0, s68, 0x12000
	s_addc_u32 s1, s69, 0
	global_load_dword v153, v233, s[0:1]
	global_load_dword v157, v233, s[0:1] offset:64
	global_load_dword v161, v233, s[0:1] offset:128
	global_load_dword v165, v233, s[0:1] offset:192
	s_add_u32 s0, s68, 0x13000
	s_addc_u32 s1, s69, 0
	global_load_dword v154, v233, s[0:1]
	global_load_dword v158, v233, s[0:1] offset:64
	global_load_dword v162, v233, s[0:1] offset:128
	global_load_dword v171, v233, s[0:1] offset:192
	v_add_u32_e32 v133, v130, v228
	ds_read_b128 v[190:193], v133
	ds_read_b128 v[194:197], v133 offset:2048
	ds_read_b128 v[198:201], v133 offset:4096
	ds_read_b128 v[202:205], v133 offset:6144
	v_add_u32_e32 v189, v128, v228
	ds_read_b128 v[206:209], v189 offset:32768
	ds_read_b128 v[210:213], v189 offset:34816
	ds_read_b128 v[214:217], v189 offset:36864
	ds_read_b128 v[218:221], v189 offset:38912
	s_setprio 1
	s_waitcnt lgkmcnt(0)
	v_mfma_f32_16x16x32_bf16 v[0:3], v[190:193], v[206:209], v[0:3]
	v_mfma_f32_16x16x32_bf16 v[4:7], v[190:193], v[210:213], v[4:7]
	v_mfma_f32_16x16x32_bf16 v[8:11], v[190:193], v[214:217], v[8:11]
	v_mfma_f32_16x16x32_bf16 v[12:15], v[190:193], v[218:221], v[12:15]
	v_mfma_f32_16x16x32_bf16 v[16:19], v[194:197], v[206:209], v[16:19]
	v_mfma_f32_16x16x32_bf16 v[20:23], v[194:197], v[210:213], v[20:23]
	v_mfma_f32_16x16x32_bf16 v[24:27], v[194:197], v[214:217], v[24:27]
	v_mfma_f32_16x16x32_bf16 v[28:31], v[194:197], v[218:221], v[28:31]
	v_mfma_f32_16x16x32_bf16 v[32:35], v[198:201], v[206:209], v[32:35]
	v_mfma_f32_16x16x32_bf16 v[36:39], v[198:201], v[210:213], v[36:39]
	v_mfma_f32_16x16x32_bf16 v[40:43], v[198:201], v[214:217], v[40:43]
	v_mfma_f32_16x16x32_bf16 v[44:47], v[198:201], v[218:221], v[44:47]
	v_mfma_f32_16x16x32_bf16 v[48:51], v[202:205], v[206:209], v[48:51]
	v_mfma_f32_16x16x32_bf16 v[52:55], v[202:205], v[210:213], v[52:55]
	v_mfma_f32_16x16x32_bf16 v[56:59], v[202:205], v[214:217], v[56:59]
	v_mfma_f32_16x16x32_bf16 v[60:63], v[202:205], v[218:221], v[60:63]
	s_setprio 0
	ds_read_b128 v[190:193], v133 offset:8192
	ds_read_b128 v[194:197], v133 offset:10240
	ds_read_b128 v[198:201], v133 offset:12288
	ds_read_b128 v[202:205], v133 offset:14336
	s_setprio 1
	s_waitcnt lgkmcnt(0)
	v_mfma_f32_16x16x32_bf16 v[64:67], v[190:193], v[206:209], v[64:67]
	v_mfma_f32_16x16x32_bf16 v[68:71], v[190:193], v[210:213], v[68:71]
	v_mfma_f32_16x16x32_bf16 v[72:75], v[190:193], v[214:217], v[72:75]
	v_mfma_f32_16x16x32_bf16 v[76:79], v[190:193], v[218:221], v[76:79]
	v_mfma_f32_16x16x32_bf16 v[80:83], v[194:197], v[206:209], v[80:83]
	v_mfma_f32_16x16x32_bf16 v[84:87], v[194:197], v[210:213], v[84:87]
	v_mfma_f32_16x16x32_bf16 v[88:91], v[194:197], v[214:217], v[88:91]
	v_mfma_f32_16x16x32_bf16 v[92:95], v[194:197], v[218:221], v[92:95]
	v_mfma_f32_16x16x32_bf16 v[96:99], v[198:201], v[206:209], v[96:99]
	v_mfma_f32_16x16x32_bf16 v[100:103], v[198:201], v[210:213], v[100:103]
	v_mfma_f32_16x16x32_bf16 v[104:107], v[198:201], v[214:217], v[104:107]
	v_mfma_f32_16x16x32_bf16 v[108:111], v[198:201], v[218:221], v[108:111]
	v_mfma_f32_16x16x32_bf16 v[112:115], v[202:205], v[206:209], v[112:115]
	v_mfma_f32_16x16x32_bf16 v[116:119], v[202:205], v[210:213], v[116:119]
	v_mfma_f32_16x16x32_bf16 v[120:123], v[202:205], v[214:217], v[120:123]
	v_mfma_f32_16x16x32_bf16 v[124:127], v[202:205], v[218:221], v[124:127]
	s_setprio 0
	v_and_b32_e32 v229, 0xcf, v224
	v_or_b32_e32 v229, v169, v229
	v_readlane_b32 s1, v254, 62
	s_movk_i32 s0, 0x1fff
	v_add_u32_e32 v216, 0xffffe000, v170
	v_cmp_lt_i32_e32 vcc, s0, v170
	v_lshrrev_b32_e32 v216, 10, v216
	v_add_u32_e32 v216, 1, v216
	v_cndmask_b32_e32 v216, 0, v216, vcc
	v_mov_b64_e32 v[212:213], s[66:67]
	v_add_u32_e32 v216, s1, v216
	s_movk_i32 s0, 0x6000
	v_mad_u64_u32 v[212:213], s[0:1], v216, s0, v[212:213]
	s_mov_b64 s[0:1], 0x5000
	v_lshl_add_u64 v[212:213], v[212:213], 0, s[0:1]
	v_mov_b32_e32 v215, 0
	v_lshlrev_b32_e32 v214, 2, v229
	v_lshl_add_u64 v[212:213], v[212:213], 0, v[214:215]
	global_load_dword v208, v[212:213], off
	global_load_dword v209, v[212:213], off offset:64
	global_load_dword v210, v[212:213], off offset:128
	global_load_dword v211, v[212:213], off offset:192
	s_add_u32 s0, s68, 0x20000
	s_addc_u32 s1, s69, 0
	global_load_dword v172, v233, s[0:1]
	global_load_dword v176, v233, s[0:1] offset:64
	global_load_dword v180, v233, s[0:1] offset:128
	global_load_dword v184, v233, s[0:1] offset:192
	s_add_u32 s0, s68, 0x21000
	s_addc_u32 s1, s69, 0
	global_load_dword v173, v233, s[0:1]
	global_load_dword v177, v233, s[0:1] offset:64
	global_load_dword v181, v233, s[0:1] offset:128
	global_load_dword v185, v233, s[0:1] offset:192
	s_add_u32 s0, s68, 0x22000
	s_addc_u32 s1, s69, 0
	global_load_dword v174, v233, s[0:1]
	global_load_dword v178, v233, s[0:1] offset:64
	global_load_dword v182, v233, s[0:1] offset:128
	global_load_dword v186, v233, s[0:1] offset:192
	s_add_u32 s0, s68, 0x23000
	s_addc_u32 s1, s69, 0
	global_load_dword v175, v233, s[0:1]
	global_load_dword v179, v233, s[0:1] offset:64
	global_load_dword v183, v233, s[0:1] offset:128
	global_load_dword v187, v233, s[0:1] offset:192
	s_add_u32 s0, s68, 0x30000
	s_addc_u32 s1, s69, 0
	global_load_dword v188, v233, s[0:1]
	global_load_dword v192, v233, s[0:1] offset:64
	global_load_dword v196, v233, s[0:1] offset:128
	global_load_dword v200, v233, s[0:1] offset:192
	s_add_u32 s0, s68, 0x31000
	s_addc_u32 s1, s69, 0
	global_load_dword v189, v233, s[0:1]
	global_load_dword v193, v233, s[0:1] offset:64
	global_load_dword v197, v233, s[0:1] offset:128
	global_load_dword v201, v233, s[0:1] offset:192
	s_add_u32 s0, s68, 0x32000
	s_addc_u32 s1, s69, 0
	global_load_dword v190, v233, s[0:1]
	global_load_dword v194, v233, s[0:1] offset:64
	global_load_dword v198, v233, s[0:1] offset:128
	global_load_dword v202, v233, s[0:1] offset:192
	s_add_u32 s0, s68, 0x33000
	s_addc_u32 s1, s69, 0
	global_load_dword v191, v233, s[0:1]
	global_load_dword v195, v233, s[0:1] offset:64
	global_load_dword v199, v233, s[0:1] offset:128
	global_load_dword v203, v233, s[0:1] offset:192
	s_waitcnt vmcnt(32)
	v_fmac_f32_e32 v131, v0, v208
	v_fmac_f32_e32 v132, v1, v208
	v_fmac_f32_e32 v134, v2, v208
	v_fmac_f32_e32 v135, v3, v208
	v_fmac_f32_e32 v136, v4, v209
	v_fmac_f32_e32 v137, v5, v209
	v_fmac_f32_e32 v138, v6, v209
	v_fmac_f32_e32 v139, v7, v209
	v_fmac_f32_e32 v140, v8, v210
	v_fmac_f32_e32 v141, v9, v210
	v_fmac_f32_e32 v142, v10, v210
	v_fmac_f32_e32 v143, v11, v210
	v_fmac_f32_e32 v144, v12, v211
	v_fmac_f32_e32 v145, v13, v211
	v_fmac_f32_e32 v149, v14, v211
	v_fmac_f32_e32 v150, v15, v211
	v_fmac_f32_e32 v151, v16, v208
	v_fmac_f32_e32 v152, v17, v208
	v_fmac_f32_e32 v153, v18, v208
	v_fmac_f32_e32 v154, v19, v208
	v_fmac_f32_e32 v155, v20, v209
	v_fmac_f32_e32 v156, v21, v209
	v_fmac_f32_e32 v157, v22, v209
	v_fmac_f32_e32 v158, v23, v209
	v_fmac_f32_e32 v159, v24, v210
	v_fmac_f32_e32 v160, v25, v210
	v_fmac_f32_e32 v161, v26, v210
	v_fmac_f32_e32 v162, v27, v210
	v_fmac_f32_e32 v163, v28, v211
	v_fmac_f32_e32 v164, v29, v211
	v_fmac_f32_e32 v165, v30, v211
	v_fmac_f32_e32 v171, v31, v211
	s_add_u32 s0, s68, 0x40000
	s_addc_u32 s1, s69, 0
	global_load_dword v0, v233, s[0:1]
	global_load_dword v4, v233, s[0:1] offset:64
	global_load_dword v8, v233, s[0:1] offset:128
	global_load_dword v12, v233, s[0:1] offset:192
	s_add_u32 s0, s68, 0x41000
	s_addc_u32 s1, s69, 0
	global_load_dword v1, v233, s[0:1]
	global_load_dword v5, v233, s[0:1] offset:64
	global_load_dword v9, v233, s[0:1] offset:128
	global_load_dword v13, v233, s[0:1] offset:192
	s_add_u32 s0, s68, 0x42000
	s_addc_u32 s1, s69, 0
	global_load_dword v2, v233, s[0:1]
	global_load_dword v6, v233, s[0:1] offset:64
	global_load_dword v10, v233, s[0:1] offset:128
	global_load_dword v14, v233, s[0:1] offset:192
	s_add_u32 s0, s68, 0x43000
	s_addc_u32 s1, s69, 0
	global_load_dword v3, v233, s[0:1]
	global_load_dword v7, v233, s[0:1] offset:64
	global_load_dword v11, v233, s[0:1] offset:128
	global_load_dword v15, v233, s[0:1] offset:192
	s_add_u32 s0, s68, 0x50000
	s_addc_u32 s1, s69, 0
	global_load_dword v16, v233, s[0:1]
	global_load_dword v20, v233, s[0:1] offset:64
	global_load_dword v24, v233, s[0:1] offset:128
	global_load_dword v28, v233, s[0:1] offset:192
	s_add_u32 s0, s68, 0x51000
	s_addc_u32 s1, s69, 0
	global_load_dword v17, v233, s[0:1]
	global_load_dword v21, v233, s[0:1] offset:64
	global_load_dword v25, v233, s[0:1] offset:128
	global_load_dword v29, v233, s[0:1] offset:192
	s_add_u32 s0, s68, 0x52000
	s_addc_u32 s1, s69, 0
	global_load_dword v18, v233, s[0:1]
	global_load_dword v22, v233, s[0:1] offset:64
	global_load_dword v26, v233, s[0:1] offset:128
	global_load_dword v30, v233, s[0:1] offset:192
	s_add_u32 s0, s68, 0x53000
	s_addc_u32 s1, s69, 0
	global_load_dword v19, v233, s[0:1]
	global_load_dword v23, v233, s[0:1] offset:64
	global_load_dword v27, v233, s[0:1] offset:128
	global_load_dword v31, v233, s[0:1] offset:192
	s_waitcnt vmcnt(32)
	v_fmac_f32_e32 v172, v32, v208
	v_fmac_f32_e32 v173, v33, v208
	v_fmac_f32_e32 v174, v34, v208
	v_fmac_f32_e32 v175, v35, v208
	v_fmac_f32_e32 v176, v36, v209
	v_fmac_f32_e32 v177, v37, v209
	v_fmac_f32_e32 v178, v38, v209
	v_fmac_f32_e32 v179, v39, v209
	v_fmac_f32_e32 v180, v40, v210
	v_fmac_f32_e32 v181, v41, v210
	v_fmac_f32_e32 v182, v42, v210
	v_fmac_f32_e32 v183, v43, v210
	v_fmac_f32_e32 v184, v44, v211
	v_fmac_f32_e32 v185, v45, v211
	v_fmac_f32_e32 v186, v46, v211
	v_fmac_f32_e32 v187, v47, v211
	v_fmac_f32_e32 v188, v48, v208
	v_fmac_f32_e32 v189, v49, v208
	v_fmac_f32_e32 v190, v50, v208
	v_fmac_f32_e32 v191, v51, v208
	v_fmac_f32_e32 v192, v52, v209
	v_fmac_f32_e32 v193, v53, v209
	v_fmac_f32_e32 v194, v54, v209
	v_fmac_f32_e32 v195, v55, v209
	v_fmac_f32_e32 v196, v56, v210
	v_fmac_f32_e32 v197, v57, v210
	v_fmac_f32_e32 v198, v58, v210
	v_fmac_f32_e32 v199, v59, v210
	v_fmac_f32_e32 v200, v60, v211
	v_fmac_f32_e32 v201, v61, v211
	v_fmac_f32_e32 v202, v62, v211
	v_fmac_f32_e32 v203, v63, v211
	s_add_u32 s0, s68, 0x60000
	s_addc_u32 s1, s69, 0
	global_load_dword v32, v233, s[0:1]
	global_load_dword v36, v233, s[0:1] offset:64
	global_load_dword v40, v233, s[0:1] offset:128
	global_load_dword v44, v233, s[0:1] offset:192
	s_add_u32 s0, s68, 0x61000
	s_addc_u32 s1, s69, 0
	global_load_dword v33, v233, s[0:1]
	global_load_dword v37, v233, s[0:1] offset:64
	global_load_dword v41, v233, s[0:1] offset:128
	global_load_dword v45, v233, s[0:1] offset:192
	s_add_u32 s0, s68, 0x62000
	s_addc_u32 s1, s69, 0
	global_load_dword v34, v233, s[0:1]
	global_load_dword v38, v233, s[0:1] offset:64
	global_load_dword v42, v233, s[0:1] offset:128
	global_load_dword v46, v233, s[0:1] offset:192
	s_add_u32 s0, s68, 0x63000
	s_addc_u32 s1, s69, 0
	global_load_dword v35, v233, s[0:1]
	global_load_dword v39, v233, s[0:1] offset:64
	global_load_dword v43, v233, s[0:1] offset:128
	global_load_dword v47, v233, s[0:1] offset:192
	s_add_u32 s0, s68, 0x70000
	s_addc_u32 s1, s69, 0
	global_load_dword v48, v233, s[0:1]
	global_load_dword v52, v233, s[0:1] offset:64
	global_load_dword v56, v233, s[0:1] offset:128
	global_load_dword v60, v233, s[0:1] offset:192
	s_add_u32 s0, s68, 0x71000
	s_addc_u32 s1, s69, 0
	global_load_dword v49, v233, s[0:1]
	global_load_dword v53, v233, s[0:1] offset:64
	global_load_dword v57, v233, s[0:1] offset:128
	global_load_dword v61, v233, s[0:1] offset:192
	s_add_u32 s0, s68, 0x72000
	s_addc_u32 s1, s69, 0
	global_load_dword v50, v233, s[0:1]
	global_load_dword v54, v233, s[0:1] offset:64
	global_load_dword v58, v233, s[0:1] offset:128
	global_load_dword v62, v233, s[0:1] offset:192
	s_add_u32 s0, s68, 0x73000
	s_addc_u32 s1, s69, 0
	global_load_dword v51, v233, s[0:1]
	global_load_dword v55, v233, s[0:1] offset:64
	global_load_dword v59, v233, s[0:1] offset:128
	global_load_dword v63, v233, s[0:1] offset:192
	s_waitcnt vmcnt(32)
	v_fmac_f32_e32 v0, v64, v208
	v_fmac_f32_e32 v1, v65, v208
	v_fmac_f32_e32 v2, v66, v208
	v_fmac_f32_e32 v3, v67, v208
	v_fmac_f32_e32 v4, v68, v209
	v_fmac_f32_e32 v5, v69, v209
	v_fmac_f32_e32 v6, v70, v209
	v_fmac_f32_e32 v7, v71, v209
	v_fmac_f32_e32 v8, v72, v210
	v_fmac_f32_e32 v9, v73, v210
	v_fmac_f32_e32 v10, v74, v210
	v_fmac_f32_e32 v11, v75, v210
	v_fmac_f32_e32 v12, v76, v211
	v_fmac_f32_e32 v13, v77, v211
	v_fmac_f32_e32 v14, v78, v211
	v_fmac_f32_e32 v15, v79, v211
	v_fmac_f32_e32 v16, v80, v208
	v_fmac_f32_e32 v17, v81, v208
	v_fmac_f32_e32 v18, v82, v208
	v_fmac_f32_e32 v19, v83, v208
	v_fmac_f32_e32 v20, v84, v209
	v_fmac_f32_e32 v21, v85, v209
	v_fmac_f32_e32 v22, v86, v209
	v_fmac_f32_e32 v23, v87, v209
	v_fmac_f32_e32 v24, v88, v210
	v_fmac_f32_e32 v25, v89, v210
	v_fmac_f32_e32 v26, v90, v210
	v_fmac_f32_e32 v27, v91, v210
	v_fmac_f32_e32 v28, v92, v211
	v_fmac_f32_e32 v29, v93, v211
	v_fmac_f32_e32 v30, v94, v211
	v_fmac_f32_e32 v31, v95, v211
	s_waitcnt vmcnt(0)
	v_fmac_f32_e32 v32, v96, v208
	v_fmac_f32_e32 v33, v97, v208
	v_fmac_f32_e32 v34, v98, v208
	v_fmac_f32_e32 v35, v99, v208
	v_fmac_f32_e32 v36, v100, v209
	v_fmac_f32_e32 v37, v101, v209
	v_fmac_f32_e32 v38, v102, v209
	v_fmac_f32_e32 v39, v103, v209
	v_fmac_f32_e32 v40, v104, v210
	v_fmac_f32_e32 v41, v105, v210
	v_fmac_f32_e32 v42, v106, v210
	v_fmac_f32_e32 v43, v107, v210
	v_fmac_f32_e32 v44, v108, v211
	v_fmac_f32_e32 v45, v109, v211
	v_fmac_f32_e32 v46, v110, v211
	v_fmac_f32_e32 v47, v111, v211
	v_fmac_f32_e32 v48, v112, v208
	v_fmac_f32_e32 v49, v113, v208
	v_fmac_f32_e32 v50, v114, v208
	v_fmac_f32_e32 v51, v115, v208
	v_fmac_f32_e32 v52, v116, v209
	v_fmac_f32_e32 v53, v117, v209
	v_fmac_f32_e32 v54, v118, v209
	v_fmac_f32_e32 v55, v119, v209
	v_fmac_f32_e32 v56, v120, v210
	v_fmac_f32_e32 v57, v121, v210
	v_fmac_f32_e32 v58, v122, v210
	v_fmac_f32_e32 v59, v123, v210
	v_fmac_f32_e32 v60, v124, v211
	v_fmac_f32_e32 v61, v125, v211
	v_fmac_f32_e32 v62, v126, v211
	v_fmac_f32_e32 v63, v127, v211
	s_mov_b32 s0, s68
	s_mov_b32 s1, s69
	global_store_dword v233, v131, s[0:1]
	global_store_dword v233, v136, s[0:1] offset:64
	global_store_dword v233, v140, s[0:1] offset:128
	global_store_dword v233, v144, s[0:1] offset:192
	s_add_u32 s0, s68, 0x1000
	s_addc_u32 s1, s69, 0
	global_store_dword v233, v132, s[0:1]
	global_store_dword v233, v137, s[0:1] offset:64
	global_store_dword v233, v141, s[0:1] offset:128
	global_store_dword v233, v145, s[0:1] offset:192
	s_add_u32 s0, s68, 0x2000
	s_addc_u32 s1, s69, 0
	global_store_dword v233, v134, s[0:1]
	global_store_dword v233, v138, s[0:1] offset:64
	global_store_dword v233, v142, s[0:1] offset:128
	global_store_dword v233, v149, s[0:1] offset:192
	s_add_u32 s0, s68, 0x3000
	s_addc_u32 s1, s69, 0
	global_store_dword v233, v135, s[0:1]
	global_store_dword v233, v139, s[0:1] offset:64
	global_store_dword v233, v143, s[0:1] offset:128
	global_store_dword v233, v150, s[0:1] offset:192
	s_add_u32 s0, s68, 0x10000
	s_addc_u32 s1, s69, 0
	global_store_dword v233, v151, s[0:1]
	global_store_dword v233, v155, s[0:1] offset:64
	global_store_dword v233, v159, s[0:1] offset:128
	global_store_dword v233, v163, s[0:1] offset:192
	s_add_u32 s0, s68, 0x11000
	s_addc_u32 s1, s69, 0
	global_store_dword v233, v152, s[0:1]
	global_store_dword v233, v156, s[0:1] offset:64
	global_store_dword v233, v160, s[0:1] offset:128
	global_store_dword v233, v164, s[0:1] offset:192
	s_add_u32 s0, s68, 0x12000
	s_addc_u32 s1, s69, 0
	global_store_dword v233, v153, s[0:1]
	global_store_dword v233, v157, s[0:1] offset:64
	global_store_dword v233, v161, s[0:1] offset:128
	global_store_dword v233, v165, s[0:1] offset:192
	s_add_u32 s0, s68, 0x13000
	s_addc_u32 s1, s69, 0
	global_store_dword v233, v154, s[0:1]
	global_store_dword v233, v158, s[0:1] offset:64
	global_store_dword v233, v162, s[0:1] offset:128
	global_store_dword v233, v171, s[0:1] offset:192
	s_add_u32 s0, s68, 0x20000
	s_addc_u32 s1, s69, 0
	global_store_dword v233, v172, s[0:1]
	global_store_dword v233, v176, s[0:1] offset:64
	global_store_dword v233, v180, s[0:1] offset:128
	global_store_dword v233, v184, s[0:1] offset:192
	s_add_u32 s0, s68, 0x21000
	s_addc_u32 s1, s69, 0
	global_store_dword v233, v173, s[0:1]
	global_store_dword v233, v177, s[0:1] offset:64
	global_store_dword v233, v181, s[0:1] offset:128
	global_store_dword v233, v185, s[0:1] offset:192
	s_add_u32 s0, s68, 0x22000
	s_addc_u32 s1, s69, 0
	global_store_dword v233, v174, s[0:1]
	global_store_dword v233, v178, s[0:1] offset:64
	global_store_dword v233, v182, s[0:1] offset:128
	global_store_dword v233, v186, s[0:1] offset:192
	s_add_u32 s0, s68, 0x23000
	s_addc_u32 s1, s69, 0
	global_store_dword v233, v175, s[0:1]
	global_store_dword v233, v179, s[0:1] offset:64
	global_store_dword v233, v183, s[0:1] offset:128
	global_store_dword v233, v187, s[0:1] offset:192
	s_add_u32 s0, s68, 0x30000
	s_addc_u32 s1, s69, 0
	global_store_dword v233, v188, s[0:1]
	global_store_dword v233, v192, s[0:1] offset:64
	global_store_dword v233, v196, s[0:1] offset:128
	global_store_dword v233, v200, s[0:1] offset:192
	s_add_u32 s0, s68, 0x31000
	s_addc_u32 s1, s69, 0
	global_store_dword v233, v189, s[0:1]
	global_store_dword v233, v193, s[0:1] offset:64
	global_store_dword v233, v197, s[0:1] offset:128
	global_store_dword v233, v201, s[0:1] offset:192
	s_add_u32 s0, s68, 0x32000
	s_addc_u32 s1, s69, 0
	global_store_dword v233, v190, s[0:1]
	global_store_dword v233, v194, s[0:1] offset:64
	global_store_dword v233, v198, s[0:1] offset:128
	global_store_dword v233, v202, s[0:1] offset:192
	s_add_u32 s0, s68, 0x33000
	s_addc_u32 s1, s69, 0
	global_store_dword v233, v191, s[0:1]
	global_store_dword v233, v195, s[0:1] offset:64
	global_store_dword v233, v199, s[0:1] offset:128
	global_store_dword v233, v203, s[0:1] offset:192
	s_add_u32 s0, s68, 0x40000
	s_addc_u32 s1, s69, 0
	global_store_dword v233, v0, s[0:1]
	global_store_dword v233, v4, s[0:1] offset:64
	global_store_dword v233, v8, s[0:1] offset:128
	global_store_dword v233, v12, s[0:1] offset:192
	s_add_u32 s0, s68, 0x41000
	s_addc_u32 s1, s69, 0
	global_store_dword v233, v1, s[0:1]
	global_store_dword v233, v5, s[0:1] offset:64
	global_store_dword v233, v9, s[0:1] offset:128
	global_store_dword v233, v13, s[0:1] offset:192
	s_add_u32 s0, s68, 0x42000
	s_addc_u32 s1, s69, 0
	global_store_dword v233, v2, s[0:1]
	global_store_dword v233, v6, s[0:1] offset:64
	global_store_dword v233, v10, s[0:1] offset:128
	global_store_dword v233, v14, s[0:1] offset:192
	s_add_u32 s0, s68, 0x43000
	s_addc_u32 s1, s69, 0
	global_store_dword v233, v3, s[0:1]
	global_store_dword v233, v7, s[0:1] offset:64
	global_store_dword v233, v11, s[0:1] offset:128
	global_store_dword v233, v15, s[0:1] offset:192
	s_add_u32 s0, s68, 0x50000
	s_addc_u32 s1, s69, 0
	global_store_dword v233, v16, s[0:1]
	global_store_dword v233, v20, s[0:1] offset:64
	global_store_dword v233, v24, s[0:1] offset:128
	global_store_dword v233, v28, s[0:1] offset:192
	s_add_u32 s0, s68, 0x51000
	s_addc_u32 s1, s69, 0
	global_store_dword v233, v17, s[0:1]
	global_store_dword v233, v21, s[0:1] offset:64
	global_store_dword v233, v25, s[0:1] offset:128
	global_store_dword v233, v29, s[0:1] offset:192
	s_add_u32 s0, s68, 0x52000
	s_addc_u32 s1, s69, 0
	global_store_dword v233, v18, s[0:1]
	global_store_dword v233, v22, s[0:1] offset:64
	global_store_dword v233, v26, s[0:1] offset:128
	global_store_dword v233, v30, s[0:1] offset:192
	s_add_u32 s0, s68, 0x53000
	s_addc_u32 s1, s69, 0
	global_store_dword v233, v19, s[0:1]
	global_store_dword v233, v23, s[0:1] offset:64
	global_store_dword v233, v27, s[0:1] offset:128
	global_store_dword v233, v31, s[0:1] offset:192
	s_add_u32 s0, s68, 0x60000
	s_addc_u32 s1, s69, 0
	global_store_dword v233, v32, s[0:1]
	global_store_dword v233, v36, s[0:1] offset:64
	global_store_dword v233, v40, s[0:1] offset:128
	global_store_dword v233, v44, s[0:1] offset:192
	s_add_u32 s0, s68, 0x61000
	s_addc_u32 s1, s69, 0
	global_store_dword v233, v33, s[0:1]
	global_store_dword v233, v37, s[0:1] offset:64
	global_store_dword v233, v41, s[0:1] offset:128
	global_store_dword v233, v45, s[0:1] offset:192
	s_add_u32 s0, s68, 0x62000
	s_addc_u32 s1, s69, 0
	global_store_dword v233, v34, s[0:1]
	global_store_dword v233, v38, s[0:1] offset:64
	global_store_dword v233, v42, s[0:1] offset:128
	global_store_dword v233, v46, s[0:1] offset:192
	s_add_u32 s0, s68, 0x63000
	s_addc_u32 s1, s69, 0
	global_store_dword v233, v35, s[0:1]
	global_store_dword v233, v39, s[0:1] offset:64
	global_store_dword v233, v43, s[0:1] offset:128
	global_store_dword v233, v47, s[0:1] offset:192
	s_add_u32 s0, s68, 0x70000
	s_addc_u32 s1, s69, 0
	global_store_dword v233, v48, s[0:1]
	global_store_dword v233, v52, s[0:1] offset:64
	global_store_dword v233, v56, s[0:1] offset:128
	global_store_dword v233, v60, s[0:1] offset:192
	s_add_u32 s0, s68, 0x71000
	s_addc_u32 s1, s69, 0
	global_store_dword v233, v49, s[0:1]
	global_store_dword v233, v53, s[0:1] offset:64
	global_store_dword v233, v57, s[0:1] offset:128
	global_store_dword v233, v61, s[0:1] offset:192
	s_add_u32 s0, s68, 0x72000
	s_addc_u32 s1, s69, 0
	global_store_dword v233, v50, s[0:1]
	global_store_dword v233, v54, s[0:1] offset:64
	global_store_dword v233, v58, s[0:1] offset:128
	global_store_dword v233, v62, s[0:1] offset:192
	s_add_u32 s0, s68, 0x73000
	s_addc_u32 s1, s69, 0
	global_store_dword v233, v51, s[0:1]
	global_store_dword v233, v55, s[0:1] offset:64
	global_store_dword v233, v59, s[0:1] offset:128
	global_store_dword v233, v63, s[0:1] offset:192
	s_andn2_b64 exec, exec, s[46:47]
	s_cbranch_execz .LBB0_237
.LBB0_225:
	v_mov_b32_e32 v32, v224
	v_mov_b32_e32 v170, v146
	v_and_b32_e32 v0, 31, v32
	v_lshrrev_b32_e32 v1, 1, v32
	v_and_or_b32 v0, v1, s59, v0
	v_lshlrev_b32_e32 v182, 7, v0
	v_lshlrev_b32_e32 v0, 7, v32
	v_and_b32_e32 v183, 0x6f80, v0
	v_lshrrev_b32_e32 v0, 5, v32
	v_bfe_u32 v2, v32, 1, 3
	v_bfe_u32 v1, v32, 5, 1
	v_bitop3_b32 v0, v0, v2, 1 bitop3:0x6c
	v_lshlrev_b32_e32 v184, 4, v0
	v_bitop3_b32 v0, v1, v2, 2 bitop3:0x36
	v_lshlrev_b32_e32 v181, 4, v0
	v_bitop3_b32 v0, v1, v2, 4 bitop3:0x36
	v_ashrrev_i32_e32 v188, 3, v32
	v_add_u32_e32 v3, 0x200, v32
	v_add_u32_e32 v4, 0x400, v32
	v_add_u32_e32 v5, 0x600, v32
	v_lshlrev_b32_e32 v172, 4, v0
	v_bitop3_b32 v0, v1, v2, 6 bitop3:0x36
	v_mov_b32_e32 v169, v148
	s_movk_i32 s0, 0xff
	v_lshrrev_b32_e32 v33, 4, v32
	v_ashrrev_i32_e32 v187, 3, v3
	v_ashrrev_i32_e32 v186, 3, v4
	v_ashrrev_i32_e32 v185, 3, v5
	v_lshrrev_b32_e32 v176, 3, v32
	v_lshrrev_b32_e32 v175, 3, v3
	v_lshrrev_b32_e32 v174, 3, v4
	v_lshrrev_b32_e32 v173, 3, v5
	v_lshlrev_b32_e32 v171, 4, v0
	v_add_u32_e32 v0, v188, v170
	v_cmp_gt_i32_e32 vcc, s73, v32
	v_cmp_lt_i32_e64 s[0:1], s0, v32
	v_xor_b32_e32 v132, v33, v32
	v_lshlrev_b32_e32 v180, 4, v32
	v_lshlrev_b32_e32 v178, 4, v4
	v_ashrrev_i32_e32 v1, 31, v0
	v_add_u32_e32 v2, v187, v170
	v_add_u32_e32 v4, v186, v170
	v_add_u32_e32 v6, v185, v170
	v_add_u32_e32 v8, v176, v170
	v_add_u32_e32 v10, v175, v170
	v_add_u32_e32 v12, v174, v170
	v_add_u32_e32 v14, v173, v170
	v_add_u32_e32 v16, v188, v169
	v_add_u32_e32 v18, v187, v169
	v_add_u32_e32 v20, v186, v169
	v_add_u32_e32 v22, v185, v169
	v_add_u32_e32 v24, v176, v169
	v_add_u32_e32 v26, v175, v169
	v_add_u32_e32 v28, v174, v169
	v_add_u32_e32 v30, v173, v169
	v_bitop3_b32 v32, v33, 7, v32 bitop3:0x48
	v_lshlrev_b32_e32 v179, 4, v3
	v_lshlrev_b32_e32 v177, 4, v5
	v_ashrrev_i32_e32 v3, 31, v2
	v_ashrrev_i32_e32 v5, 31, v4
	v_ashrrev_i32_e32 v7, 31, v6
	v_ashrrev_i32_e32 v9, 31, v8
	v_ashrrev_i32_e32 v11, 31, v10
	v_ashrrev_i32_e32 v13, 31, v12
	v_ashrrev_i32_e32 v15, 31, v14
	v_lshlrev_b64 v[0:1], 13, v[0:1]
	v_ashrrev_i32_e32 v17, 31, v16
	v_ashrrev_i32_e32 v19, 31, v18
	v_ashrrev_i32_e32 v21, 31, v20
	v_ashrrev_i32_e32 v23, 31, v22
	v_ashrrev_i32_e32 v25, 31, v24
	v_ashrrev_i32_e32 v27, 31, v26
	v_ashrrev_i32_e32 v29, 31, v28
	v_ashrrev_i32_e32 v31, 31, v30
	v_lshlrev_b32_e32 v32, 4, v32
	s_waitcnt vmcnt(0)
	v_lshlrev_b64 v[2:3], 13, v[2:3]
	v_lshlrev_b64 v[4:5], 13, v[4:5]
	v_lshlrev_b64 v[6:7], 13, v[6:7]
	v_lshlrev_b64 v[8:9], 13, v[8:9]
	v_lshlrev_b64 v[10:11], 13, v[10:11]
	v_lshlrev_b64 v[12:13], 13, v[12:13]
	v_lshlrev_b64 v[14:15], 13, v[14:15]
	v_lshlrev_b64 v[16:17], 13, v[16:17]
	v_lshlrev_b64 v[18:19], 13, v[18:19]
	v_lshlrev_b64 v[20:21], 13, v[20:21]
	v_lshlrev_b64 v[22:23], 13, v[22:23]
	v_lshlrev_b64 v[24:25], 13, v[24:25]
	v_lshlrev_b64 v[26:27], 13, v[26:27]
	v_lshlrev_b64 v[28:29], 13, v[28:29]
	v_lshlrev_b64 v[30:31], 13, v[30:31]
	v_or_b32_e32 v0, v0, v32
	v_lshl_add_u64 v[134:135], s[42:43], 0, v[0:1]
	v_or_b32_e32 v2, v2, v32
	v_or_b32_e32 v4, v4, v32
	v_or_b32_e32 v6, v6, v32
	v_or_b32_e32 v16, v16, v32
	v_or_b32_e32 v18, v18, v32
	v_or_b32_e32 v20, v20, v32
	v_or_b32_e32 v22, v22, v32
	v_or_b32_e32 v8, v8, v32
	v_or_b32_e32 v10, v10, v32
	v_or_b32_e32 v12, v12, v32
	v_or_b32_e32 v14, v14, v32
	v_or_b32_e32 v24, v24, v32
	v_or_b32_e32 v26, v26, v32
	v_or_b32_e32 v28, v28, v32
	v_or_b32_e32 v30, v30, v32
	v_mov_b32_e32 v0, 0
	v_mov_b32_e32 v128, v147
	v_lshl_add_u64 v[136:137], s[42:43], 0, v[2:3]
	v_lshl_add_u64 v[138:139], s[42:43], 0, v[4:5]
	v_lshl_add_u64 v[140:141], s[42:43], 0, v[6:7]
	v_lshl_add_u64 v[142:143], s[44:45], 0, v[16:17]
	v_lshl_add_u64 v[144:145], s[44:45], 0, v[18:19]
	v_lshl_add_u64 v[146:147], s[44:45], 0, v[20:21]
	v_lshl_add_u64 v[148:149], s[44:45], 0, v[22:23]
	v_lshl_add_u64 v[150:151], s[42:43], 0, v[8:9]
	v_lshl_add_u64 v[152:153], s[42:43], 0, v[10:11]
	v_lshl_add_u64 v[154:155], s[42:43], 0, v[12:13]
	v_lshl_add_u64 v[156:157], s[42:43], 0, v[14:15]
	v_lshl_add_u64 v[158:159], s[44:45], 0, v[24:25]
	v_lshl_add_u64 v[160:161], s[44:45], 0, v[26:27]
	v_lshl_add_u64 v[162:163], s[44:45], 0, v[28:29]
	v_lshl_add_u64 v[164:165], s[44:45], 0, v[30:31]
	s_mov_b64 s[4:5], 0
	v_mov_b32_e32 v1, v0
	v_mov_b32_e32 v2, v0
	v_mov_b32_e32 v3, v0
	v_mov_b32_e32 v4, v0
	v_mov_b32_e32 v5, v0
	v_mov_b32_e32 v6, v0
	v_mov_b32_e32 v7, v0
	v_mov_b32_e32 v8, v0
	v_mov_b32_e32 v9, v0
	v_mov_b32_e32 v10, v0
	v_mov_b32_e32 v11, v0
	v_mov_b32_e32 v12, v0
	v_mov_b32_e32 v13, v0
	v_mov_b32_e32 v14, v0
	v_mov_b32_e32 v15, v0
	v_mov_b32_e32 v16, v0
	v_mov_b32_e32 v17, v0
	v_mov_b32_e32 v18, v0
	v_mov_b32_e32 v19, v0
	v_mov_b32_e32 v20, v0
	v_mov_b32_e32 v21, v0
	v_mov_b32_e32 v22, v0
	v_mov_b32_e32 v23, v0
	v_mov_b32_e32 v24, v0
	v_mov_b32_e32 v25, v0
	v_mov_b32_e32 v26, v0
	v_mov_b32_e32 v27, v0
	v_mov_b32_e32 v28, v0
	v_mov_b32_e32 v29, v0
	v_mov_b32_e32 v30, v0
	v_mov_b32_e32 v31, v0
	v_mov_b32_e32 v32, v0
	v_mov_b32_e32 v33, v0
	v_mov_b32_e32 v34, v0
	v_mov_b32_e32 v35, v0
	v_mov_b32_e32 v36, v0
	v_mov_b32_e32 v37, v0
	v_mov_b32_e32 v38, v0
	v_mov_b32_e32 v39, v0
	v_mov_b32_e32 v40, v0
	v_mov_b32_e32 v41, v0
	v_mov_b32_e32 v42, v0
	v_mov_b32_e32 v43, v0
	v_mov_b32_e32 v44, v0
	v_mov_b32_e32 v45, v0
	v_mov_b32_e32 v46, v0
	v_mov_b32_e32 v47, v0
	v_mov_b32_e32 v48, v0
	v_mov_b32_e32 v49, v0
	v_mov_b32_e32 v50, v0
	v_mov_b32_e32 v51, v0
	v_mov_b32_e32 v52, v0
	v_mov_b32_e32 v53, v0
	v_mov_b32_e32 v54, v0
	v_mov_b32_e32 v55, v0
	v_mov_b32_e32 v56, v0
	v_mov_b32_e32 v57, v0
	v_mov_b32_e32 v58, v0
	v_mov_b32_e32 v59, v0
	v_mov_b32_e32 v60, v0
	v_mov_b32_e32 v61, v0
	v_mov_b32_e32 v62, v0
	v_mov_b32_e32 v63, v0
	v_mov_b32_e32 v64, v0
	v_mov_b32_e32 v65, v0
	v_mov_b32_e32 v66, v0
	v_mov_b32_e32 v67, v0
	v_mov_b32_e32 v68, v0
	v_mov_b32_e32 v69, v0
	v_mov_b32_e32 v70, v0
	v_mov_b32_e32 v71, v0
	v_mov_b32_e32 v72, v0
	v_mov_b32_e32 v73, v0
	v_mov_b32_e32 v74, v0
	v_mov_b32_e32 v75, v0
	v_mov_b32_e32 v76, v0
	v_mov_b32_e32 v77, v0
	v_mov_b32_e32 v78, v0
	v_mov_b32_e32 v79, v0
	v_mov_b32_e32 v80, v0
	v_mov_b32_e32 v81, v0
	v_mov_b32_e32 v82, v0
	v_mov_b32_e32 v83, v0
	v_mov_b32_e32 v84, v0
	v_mov_b32_e32 v85, v0
	v_mov_b32_e32 v86, v0
	v_mov_b32_e32 v87, v0
	v_mov_b32_e32 v88, v0
	v_mov_b32_e32 v89, v0
	v_mov_b32_e32 v90, v0
	v_mov_b32_e32 v91, v0
	v_mov_b32_e32 v92, v0
	v_mov_b32_e32 v93, v0
	v_mov_b32_e32 v94, v0
	v_mov_b32_e32 v95, v0
	v_mov_b32_e32 v96, v0
	v_mov_b32_e32 v97, v0
	v_mov_b32_e32 v98, v0
	v_mov_b32_e32 v99, v0
	v_mov_b32_e32 v100, v0
	v_mov_b32_e32 v101, v0
	v_mov_b32_e32 v102, v0
	v_mov_b32_e32 v103, v0
	v_mov_b32_e32 v104, v0
	v_mov_b32_e32 v105, v0
	v_mov_b32_e32 v106, v0
	v_mov_b32_e32 v107, v0
	v_mov_b32_e32 v108, v0
	v_mov_b32_e32 v109, v0
	v_mov_b32_e32 v110, v0
	v_mov_b32_e32 v111, v0
	v_mov_b32_e32 v112, v0
	v_mov_b32_e32 v113, v0
	v_mov_b32_e32 v114, v0
	v_mov_b32_e32 v115, v0
	v_mov_b32_e32 v116, v0
	v_mov_b32_e32 v117, v0
	v_mov_b32_e32 v118, v0
	v_mov_b32_e32 v119, v0
	v_mov_b32_e32 v120, v0
	v_mov_b32_e32 v121, v0
	v_mov_b32_e32 v122, v0
	v_mov_b32_e32 v123, v0
	v_mov_b32_e32 v124, v0
	v_mov_b32_e32 v125, v0
	v_mov_b32_e32 v126, v0
	v_mov_b32_e32 v127, v0
	v_and_b32_e32 v229, 15, v224
	v_lshrrev_b32_e32 v230, 8, v224
	v_lshl_add_u32 v222, v230, 7, v229
	v_lshlrev_b32_e32 v222, 7, v222
	v_bfe_u32 v230, v224, 6, 2
	v_lshl_add_u32 v223, v230, 6, v229
	v_lshlrev_b32_e32 v223, 7, v223
	v_bfe_u32 v229, v224, 1, 3
	v_bfe_u32 v230, v224, 4, 2
	v_xor_b32_e32 v227, v230, v229
	v_lshlrev_b32_e32 v227, 4, v227
	v_or_b32_e32 v230, 4, v230
	v_xor_b32_e32 v228, v230, v229
	v_lshlrev_b32_e32 v228, 4, v228
	s_waitcnt vmcnt(0)
	s_barrier
	s_lshl_b32 s13, s9, 16
	s_and_saveexec_b64 s[6:7], vcc
	s_cbranch_execz .LBB0_228
	s_branch .LBB0_227

.LBB0_228:
	s_or_b64 exec, exec, s[6:7]
	s_add_i32 s6, s13, 0
	v_add_u32_e32 v131, s6, v222
	v_add_u32_e32 v130, s6, v223
	v_add_u32_e32 v133, v131, v227
	ds_read_b128 v[190:193], v133
	ds_read_b128 v[194:197], v133 offset:2048
	ds_read_b128 v[198:201], v133 offset:4096
	ds_read_b128 v[202:205], v133 offset:6144
	v_add_u32_e32 v189, v130, v227
	ds_read_b128 v[206:209], v189 offset:32768
	ds_read_b128 v[210:213], v189 offset:34816
	ds_read_b128 v[214:217], v189 offset:36864
	ds_read_b128 v[218:221], v189 offset:38912
	s_setprio 1
	s_waitcnt lgkmcnt(0)
	v_mfma_f32_16x16x32_bf16 v[0:3], v[190:193], v[206:209], v[0:3]
	v_mfma_f32_16x16x32_bf16 v[4:7], v[190:193], v[210:213], v[4:7]
	v_mfma_f32_16x16x32_bf16 v[8:11], v[190:193], v[214:217], v[8:11]
	v_mfma_f32_16x16x32_bf16 v[12:15], v[190:193], v[218:221], v[12:15]
	v_mfma_f32_16x16x32_bf16 v[16:19], v[194:197], v[206:209], v[16:19]
	v_mfma_f32_16x16x32_bf16 v[20:23], v[194:197], v[210:213], v[20:23]
	v_mfma_f32_16x16x32_bf16 v[24:27], v[194:197], v[214:217], v[24:27]
	v_mfma_f32_16x16x32_bf16 v[28:31], v[194:197], v[218:221], v[28:31]
	v_mfma_f32_16x16x32_bf16 v[32:35], v[198:201], v[206:209], v[32:35]
	v_mfma_f32_16x16x32_bf16 v[36:39], v[198:201], v[210:213], v[36:39]
	v_mfma_f32_16x16x32_bf16 v[40:43], v[198:201], v[214:217], v[40:43]
	v_mfma_f32_16x16x32_bf16 v[44:47], v[198:201], v[218:221], v[44:47]
	v_mfma_f32_16x16x32_bf16 v[48:51], v[202:205], v[206:209], v[48:51]
	v_mfma_f32_16x16x32_bf16 v[52:55], v[202:205], v[210:213], v[52:55]
	v_mfma_f32_16x16x32_bf16 v[56:59], v[202:205], v[214:217], v[56:59]
	v_mfma_f32_16x16x32_bf16 v[60:63], v[202:205], v[218:221], v[60:63]
	s_setprio 0
	ds_read_b128 v[190:193], v133 offset:8192
	ds_read_b128 v[194:197], v133 offset:10240
	ds_read_b128 v[198:201], v133 offset:12288
	ds_read_b128 v[202:205], v133 offset:14336
	s_setprio 1
	s_waitcnt lgkmcnt(0)
	v_mfma_f32_16x16x32_bf16 v[64:67], v[190:193], v[206:209], v[64:67]
	v_mfma_f32_16x16x32_bf16 v[68:71], v[190:193], v[210:213], v[68:71]
	v_mfma_f32_16x16x32_bf16 v[72:75], v[190:193], v[214:217], v[72:75]
	v_mfma_f32_16x16x32_bf16 v[76:79], v[190:193], v[218:221], v[76:79]
	v_mfma_f32_16x16x32_bf16 v[80:83], v[194:197], v[206:209], v[80:83]
	v_mfma_f32_16x16x32_bf16 v[84:87], v[194:197], v[210:213], v[84:87]
	v_mfma_f32_16x16x32_bf16 v[88:91], v[194:197], v[214:217], v[88:91]
	v_mfma_f32_16x16x32_bf16 v[92:95], v[194:197], v[218:221], v[92:95]
	v_mfma_f32_16x16x32_bf16 v[96:99], v[198:201], v[206:209], v[96:99]
	v_mfma_f32_16x16x32_bf16 v[100:103], v[198:201], v[210:213], v[100:103]
	v_mfma_f32_16x16x32_bf16 v[104:107], v[198:201], v[214:217], v[104:107]
	v_mfma_f32_16x16x32_bf16 v[108:111], v[198:201], v[218:221], v[108:111]
	v_mfma_f32_16x16x32_bf16 v[112:115], v[202:205], v[206:209], v[112:115]
	v_mfma_f32_16x16x32_bf16 v[116:119], v[202:205], v[210:213], v[116:119]
	v_mfma_f32_16x16x32_bf16 v[120:123], v[202:205], v[214:217], v[120:123]
	v_mfma_f32_16x16x32_bf16 v[124:127], v[202:205], v[218:221], v[124:127]
	s_setprio 0
	s_and_saveexec_b64 s[6:7], s[0:1]
	s_cbranch_execz .LBB0_230
	s_xor_b32 s13, s13, 0x10000
	s_add_i32 s13, s13, 0
	v_add_u32_e32 v133, s13, v180
	v_add_u32_e32 v189, s13, v179
	v_readfirstlane_b32 s14, v133
	v_lshl_add_u64 v[190:191], v[150:151], 0, s[4:5]
	s_mov_b32 m0, s14
	v_readfirstlane_b32 s14, v189
	v_add_u32_e32 v192, s13, v178
	global_load_lds_dwordx4 v[190:191], off
	v_lshl_add_u64 v[190:191], v[152:153], 0, s[4:5]
	s_mov_b32 m0, s14
	v_readfirstlane_b32 s14, v192
	v_add_u32_e32 v193, s13, v177
	global_load_lds_dwordx4 v[190:191], off
	v_lshl_add_u64 v[190:191], v[154:155], 0, s[4:5]
	s_mov_b32 m0, s14
	v_readfirstlane_b32 s13, v193
	v_add_u32_e32 v133, 0x8000, v133
	global_load_lds_dwordx4 v[190:191], off
	v_lshl_add_u64 v[190:191], v[156:157], 0, s[4:5]
	s_mov_b32 m0, s13
	v_readfirstlane_b32 s13, v133
	v_add_u32_e32 v133, 0x8000, v189
	global_load_lds_dwordx4 v[190:191], off
	v_lshl_add_u64 v[190:191], v[158:159], 0, s[4:5]
	s_mov_b32 m0, s13
	v_readfirstlane_b32 s13, v133
	v_add_u32_e32 v133, 0x8000, v192
	global_load_lds_dwordx4 v[190:191], off
	v_lshl_add_u64 v[190:191], v[160:161], 0, s[4:5]
	s_mov_b32 m0, s13
	v_readfirstlane_b32 s13, v133
	v_add_u32_e32 v133, 0x8000, v193
	global_load_lds_dwordx4 v[190:191], off
	v_lshl_add_u64 v[190:191], v[162:163], 0, s[4:5]
	s_mov_b32 m0, s13
	v_readfirstlane_b32 s13, v133
	global_load_lds_dwordx4 v[190:191], off
	v_lshl_add_u64 v[190:191], v[164:165], 0, s[4:5]
	s_mov_b32 m0, s13
	s_nop 0
	global_load_lds_dwordx4 v[190:191], off
.LBB0_230:
	s_or_b64 exec, exec, s[6:7]
	v_add_u32_e32 v133, v131, v228
	ds_read_b128 v[190:193], v133
	ds_read_b128 v[194:197], v133 offset:2048
	ds_read_b128 v[198:201], v133 offset:4096
	ds_read_b128 v[202:205], v133 offset:6144
	v_add_u32_e32 v189, v130, v228
	ds_read_b128 v[206:209], v189 offset:32768
	ds_read_b128 v[210:213], v189 offset:34816
	ds_read_b128 v[214:217], v189 offset:36864
	ds_read_b128 v[218:221], v189 offset:38912
	s_setprio 1
	s_waitcnt lgkmcnt(0)
	v_mfma_f32_16x16x32_bf16 v[0:3], v[190:193], v[206:209], v[0:3]
	v_mfma_f32_16x16x32_bf16 v[4:7], v[190:193], v[210:213], v[4:7]
	v_mfma_f32_16x16x32_bf16 v[8:11], v[190:193], v[214:217], v[8:11]
	v_mfma_f32_16x16x32_bf16 v[12:15], v[190:193], v[218:221], v[12:15]
	v_mfma_f32_16x16x32_bf16 v[16:19], v[194:197], v[206:209], v[16:19]
	v_mfma_f32_16x16x32_bf16 v[20:23], v[194:197], v[210:213], v[20:23]
	v_mfma_f32_16x16x32_bf16 v[24:27], v[194:197], v[214:217], v[24:27]
	v_mfma_f32_16x16x32_bf16 v[28:31], v[194:197], v[218:221], v[28:31]
	v_mfma_f32_16x16x32_bf16 v[32:35], v[198:201], v[206:209], v[32:35]
	v_mfma_f32_16x16x32_bf16 v[36:39], v[198:201], v[210:213], v[36:39]
	v_mfma_f32_16x16x32_bf16 v[40:43], v[198:201], v[214:217], v[40:43]
	v_mfma_f32_16x16x32_bf16 v[44:47], v[198:201], v[218:221], v[44:47]
	v_mfma_f32_16x16x32_bf16 v[48:51], v[202:205], v[206:209], v[48:51]
	v_mfma_f32_16x16x32_bf16 v[52:55], v[202:205], v[210:213], v[52:55]
	v_mfma_f32_16x16x32_bf16 v[56:59], v[202:205], v[214:217], v[56:59]
	v_mfma_f32_16x16x32_bf16 v[60:63], v[202:205], v[218:221], v[60:63]
	s_setprio 0
	ds_read_b128 v[190:193], v133 offset:8192
	ds_read_b128 v[194:197], v133 offset:10240
	ds_read_b128 v[198:201], v133 offset:12288
	ds_read_b128 v[202:205], v133 offset:14336
	s_setprio 1
	s_waitcnt lgkmcnt(0)
	v_mfma_f32_16x16x32_bf16 v[64:67], v[190:193], v[206:209], v[64:67]
	v_mfma_f32_16x16x32_bf16 v[68:71], v[190:193], v[210:213], v[68:71]
	v_mfma_f32_16x16x32_bf16 v[72:75], v[190:193], v[214:217], v[72:75]
	v_mfma_f32_16x16x32_bf16 v[76:79], v[190:193], v[218:221], v[76:79]
	v_mfma_f32_16x16x32_bf16 v[80:83], v[194:197], v[206:209], v[80:83]
	v_mfma_f32_16x16x32_bf16 v[84:87], v[194:197], v[210:213], v[84:87]
	v_mfma_f32_16x16x32_bf16 v[88:91], v[194:197], v[214:217], v[88:91]
	v_mfma_f32_16x16x32_bf16 v[92:95], v[194:197], v[218:221], v[92:95]
	v_mfma_f32_16x16x32_bf16 v[96:99], v[198:201], v[206:209], v[96:99]
	v_mfma_f32_16x16x32_bf16 v[100:103], v[198:201], v[210:213], v[100:103]
	v_mfma_f32_16x16x32_bf16 v[104:107], v[198:201], v[214:217], v[104:107]
	v_mfma_f32_16x16x32_bf16 v[108:111], v[198:201], v[218:221], v[108:111]
	v_mfma_f32_16x16x32_bf16 v[112:115], v[202:205], v[206:209], v[112:115]
	v_mfma_f32_16x16x32_bf16 v[116:119], v[202:205], v[210:213], v[116:119]
	v_mfma_f32_16x16x32_bf16 v[120:123], v[202:205], v[214:217], v[120:123]
	v_mfma_f32_16x16x32_bf16 v[124:127], v[202:205], v[218:221], v[124:127]
	s_setprio 0
	s_xor_b32 s6, s9, 1
	s_waitcnt vmcnt(0)
	s_add_u32 s4, s4, 0x80
	s_addc_u32 s5, s5, 0
	s_cmpk_lg_i32 s4, 0x1f80
	s_waitcnt vmcnt(0)
	s_barrier
	s_cbranch_scc1 .LBB0_226
	v_add_u32_e32 v147, s8, v128
	v_cmp_lt_i32_e64 s[0:1], 23, v147
	s_xor_b64 s[4:5], vcc, -1
	s_nor_b64 s[4:5], s[4:5], s[0:1]
	v_cndmask_b32_e64 v128, v147, v128, s[0:1]
	v_ashrrev_i32_e32 v130, 31, v128
	v_lshrrev_b32_e32 v130, 30, v130
	v_add_u32_e32 v130, v128, v130
	v_lshrrev_b32_e32 v131, 2, v130
	v_and_b32_e32 v130, 0xfffffc, v130
	v_sub_u32_e32 v130, v128, v130
	v_lshlrev_b32_e32 v128, 4, v132
	v_and_b32_e32 v128, 0x70, v128
	v_add_lshl_u32 v146, v131, v166, 8
	v_lshl_add_u64 v[136:137], s[38:39], 0, v[128:129]
	v_lshl_add_u64 v[134:135], s[40:41], 0, v[128:129]
	v_lshlrev_b32_e32 v148, 8, v130
	s_and_saveexec_b64 s[14:15], s[4:5]
	s_xor_b64 s[4:5], exec, s[14:15]
	s_cbranch_execz .LBB0_233
	s_lshl_b32 s7, s6, 16
	s_xor_b32 s13, s7, 0x10000
	v_add_u32_e32 v130, v146, v188
	s_add_i32 s13, s13, 0
	v_ashrrev_i32_e32 v131, 31, v130
	v_add_u32_e32 v132, v187, v146
	v_add_u32_e32 v128, s13, v180
	v_lshlrev_b64 v[130:131], 13, v[130:131]
	v_ashrrev_i32_e32 v133, 31, v132
	v_readfirstlane_b32 s14, v128
	v_add_u32_e32 v142, s13, v179
	v_lshl_add_u64 v[130:131], v[136:137], 0, v[130:131]
	v_lshlrev_b64 v[132:133], 13, v[132:133]
	s_mov_b32 m0, s14
	v_readfirstlane_b32 s14, v142
	v_lshl_add_u64 v[132:133], v[136:137], 0, v[132:133]
	v_add_u32_e32 v138, v186, v146
	global_load_lds_dwordx4 v[130:131], off
	s_mov_b32 m0, s14
	v_ashrrev_i32_e32 v139, 31, v138
	v_add_u32_e32 v140, v185, v146
	global_load_lds_dwordx4 v[132:133], off
	v_add_u32_e32 v132, s13, v178
	v_lshlrev_b64 v[138:139], 13, v[138:139]
	v_ashrrev_i32_e32 v141, 31, v140
	v_readfirstlane_b32 s14, v132
	v_add_u32_e32 v133, s13, v177
	v_add_u32_e32 v130, v148, v188
	v_lshl_add_u64 v[138:139], v[136:137], 0, v[138:139]
	v_lshlrev_b64 v[140:141], 13, v[140:141]
	s_mov_b32 m0, s14
	v_readfirstlane_b32 s13, v133
	v_ashrrev_i32_e32 v131, 31, v130
	v_add_u32_e32 v128, 0x8000, v128
	v_lshl_add_u64 v[140:141], v[136:137], 0, v[140:141]
	global_load_lds_dwordx4 v[138:139], off
	s_mov_b32 m0, s13
	v_lshlrev_b64 v[130:131], 13, v[130:131]
	v_readfirstlane_b32 s13, v128
	global_load_lds_dwordx4 v[140:141], off
	v_lshl_add_u64 v[130:131], v[134:135], 0, v[130:131]
	s_mov_b32 m0, s13
	v_add_u32_e32 v128, 0x8000, v142
	global_load_lds_dwordx4 v[130:131], off
	v_add_u32_e32 v130, v187, v148
	v_ashrrev_i32_e32 v131, 31, v130
	v_lshlrev_b64 v[130:131], 13, v[130:131]
	v_readfirstlane_b32 s13, v128
	v_lshl_add_u64 v[130:131], v[134:135], 0, v[130:131]
	s_mov_b32 m0, s13
	v_add_u32_e32 v128, 0x8000, v132
	global_load_lds_dwordx4 v[130:131], off
	v_add_u32_e32 v130, v186, v148
	v_ashrrev_i32_e32 v131, 31, v130
	v_lshlrev_b64 v[130:131], 13, v[130:131]
	v_readfirstlane_b32 s13, v128
	v_lshl_add_u64 v[130:131], v[134:135], 0, v[130:131]
	s_mov_b32 m0, s13
	v_add_u32_e32 v128, 0x8000, v133
	global_load_lds_dwordx4 v[130:131], off
	v_add_u32_e32 v130, v185, v148
	v_ashrrev_i32_e32 v131, 31, v130
	v_lshlrev_b64 v[130:131], 13, v[130:131]
	v_readfirstlane_b32 s13, v128
	v_lshl_add_u64 v[130:131], v[134:135], 0, v[130:131]
	s_mov_b32 m0, s13
	s_nop 0
	global_load_lds_dwordx4 v[130:131], off
.LBB0_233:
	s_or_saveexec_b64 s[4:5], s[4:5]
	v_mov_b32_e32 v131, s7
	s_xor_b64 exec, exec, s[4:5]
	s_lshl_b32 s6, s6, 16
	v_mov_b32_e32 v131, s6
	s_or_b64 exec, exec, s[4:5]
	v_add_u32_e32 v128, 0, v131
	v_add_u32_e32 v130, v128, v222
	v_add_u32_e32 v128, v128, v223
	v_add_u32_e32 v132, v130, v227
	ds_read_b128 v[190:193], v132
	ds_read_b128 v[194:197], v132 offset:2048
	ds_read_b128 v[198:201], v132 offset:4096
	ds_read_b128 v[202:205], v132 offset:6144
	v_add_u32_e32 v189, v128, v227
	ds_read_b128 v[206:209], v189 offset:32768
	ds_read_b128 v[210:213], v189 offset:34816
	ds_read_b128 v[214:217], v189 offset:36864
	ds_read_b128 v[218:221], v189 offset:38912
	s_and_b64 s[4:5], exec, s[0:1]
	s_or_b64 s[46:47], s[4:5], s[46:47]
	s_setprio 1
	s_waitcnt lgkmcnt(0)
	v_mfma_f32_16x16x32_bf16 v[0:3], v[190:193], v[206:209], v[0:3]
	v_mfma_f32_16x16x32_bf16 v[4:7], v[190:193], v[210:213], v[4:7]
	v_mfma_f32_16x16x32_bf16 v[8:11], v[190:193], v[214:217], v[8:11]
	v_mfma_f32_16x16x32_bf16 v[12:15], v[190:193], v[218:221], v[12:15]
	v_mfma_f32_16x16x32_bf16 v[16:19], v[194:197], v[206:209], v[16:19]
	v_mfma_f32_16x16x32_bf16 v[20:23], v[194:197], v[210:213], v[20:23]
	v_mfma_f32_16x16x32_bf16 v[24:27], v[194:197], v[214:217], v[24:27]
	v_mfma_f32_16x16x32_bf16 v[28:31], v[194:197], v[218:221], v[28:31]
	v_mfma_f32_16x16x32_bf16 v[32:35], v[198:201], v[206:209], v[32:35]
	v_mfma_f32_16x16x32_bf16 v[36:39], v[198:201], v[210:213], v[36:39]
	v_mfma_f32_16x16x32_bf16 v[40:43], v[198:201], v[214:217], v[40:43]
	v_mfma_f32_16x16x32_bf16 v[44:47], v[198:201], v[218:221], v[44:47]
	v_mfma_f32_16x16x32_bf16 v[48:51], v[202:205], v[206:209], v[48:51]
	v_mfma_f32_16x16x32_bf16 v[52:55], v[202:205], v[210:213], v[52:55]
	v_mfma_f32_16x16x32_bf16 v[56:59], v[202:205], v[214:217], v[56:59]
	v_mfma_f32_16x16x32_bf16 v[60:63], v[202:205], v[218:221], v[60:63]
	s_setprio 0
	ds_read_b128 v[190:193], v132 offset:8192
	ds_read_b128 v[194:197], v132 offset:10240
	ds_read_b128 v[198:201], v132 offset:12288
	ds_read_b128 v[202:205], v132 offset:14336
	s_setprio 1
	s_waitcnt lgkmcnt(0)
	v_mfma_f32_16x16x32_bf16 v[64:67], v[190:193], v[206:209], v[64:67]
	v_mfma_f32_16x16x32_bf16 v[68:71], v[190:193], v[210:213], v[68:71]
	v_mfma_f32_16x16x32_bf16 v[72:75], v[190:193], v[214:217], v[72:75]
	v_mfma_f32_16x16x32_bf16 v[76:79], v[190:193], v[218:221], v[76:79]
	v_mfma_f32_16x16x32_bf16 v[80:83], v[194:197], v[206:209], v[80:83]
	v_mfma_f32_16x16x32_bf16 v[84:87], v[194:197], v[210:213], v[84:87]
	v_mfma_f32_16x16x32_bf16 v[88:91], v[194:197], v[214:217], v[88:91]
	v_mfma_f32_16x16x32_bf16 v[92:95], v[194:197], v[218:221], v[92:95]
	v_mfma_f32_16x16x32_bf16 v[96:99], v[198:201], v[206:209], v[96:99]
	v_mfma_f32_16x16x32_bf16 v[100:103], v[198:201], v[210:213], v[100:103]
	v_mfma_f32_16x16x32_bf16 v[104:107], v[198:201], v[214:217], v[104:107]
	v_mfma_f32_16x16x32_bf16 v[108:111], v[198:201], v[218:221], v[108:111]
	v_mfma_f32_16x16x32_bf16 v[112:115], v[202:205], v[206:209], v[112:115]
	v_mfma_f32_16x16x32_bf16 v[116:119], v[202:205], v[210:213], v[116:119]
	v_mfma_f32_16x16x32_bf16 v[120:123], v[202:205], v[214:217], v[120:123]
	v_mfma_f32_16x16x32_bf16 v[124:127], v[202:205], v[218:221], v[124:127]
	s_setprio 0
	s_nor_b64 s[4:5], vcc, s[0:1]
	s_and_saveexec_b64 s[0:1], s[4:5]
	s_cbranch_execz .LBB0_224
	v_add_u32_e32 v132, v173, v146
	v_add_u32_e32 v138, v146, v176
	v_add_u32_e32 v140, v175, v146
	v_add_u32_e32 v142, v174, v146
	v_ashrrev_i32_e32 v133, 31, v132
	v_ashrrev_i32_e32 v139, 31, v138
	v_ashrrev_i32_e32 v141, 31, v140
	v_ashrrev_i32_e32 v143, 31, v142
	v_xor_b32_e32 v131, 0x10000, v131
	v_lshlrev_b64 v[132:133], 13, v[132:133]
	v_lshlrev_b64 v[138:139], 13, v[138:139]
	v_lshlrev_b64 v[140:141], 13, v[140:141]
	v_lshlrev_b64 v[142:143], 13, v[142:143]
	v_add_u32_e32 v131, 0, v131
	v_lshl_add_u64 v[132:133], v[136:137], 0, v[132:133]
	v_lshl_add_u64 v[138:139], v[136:137], 0, v[138:139]
	v_lshl_add_u64 v[140:141], v[136:137], 0, v[140:141]
	v_lshl_add_u64 v[136:137], v[136:137], 0, v[142:143]
	v_add_u32_e32 v142, v131, v180
	s_nop 0
	v_readfirstlane_b32 s4, v142
	s_mov_b32 m0, s4
	s_nop 0
	global_load_lds_dwordx4 v[138:139], off
	v_add_u32_e32 v138, v131, v179
	v_add_u32_e32 v139, v131, v178
	v_readfirstlane_b32 s4, v138
	s_mov_b32 m0, s4
	v_readfirstlane_b32 s4, v139
	v_add_u32_e32 v131, v131, v177
	global_load_lds_dwordx4 v[140:141], off
	s_mov_b32 m0, s4
	v_readfirstlane_b32 s4, v131
	global_load_lds_dwordx4 v[136:137], off
	s_mov_b32 m0, s4
	v_add_u32_e32 v136, 0x8000, v142
	global_load_lds_dwordx4 v[132:133], off
	v_add_u32_e32 v132, v148, v176
	v_ashrrev_i32_e32 v133, 31, v132
	v_lshlrev_b64 v[132:133], 13, v[132:133]
	v_readfirstlane_b32 s4, v136
	v_lshl_add_u64 v[132:133], v[134:135], 0, v[132:133]
	s_mov_b32 m0, s4
	v_add_u32_e32 v136, 0x8000, v138
	global_load_lds_dwordx4 v[132:133], off
	v_add_u32_e32 v132, v175, v148
	v_ashrrev_i32_e32 v133, 31, v132
	v_lshlrev_b64 v[132:133], 13, v[132:133]
	v_readfirstlane_b32 s4, v136
	v_lshl_add_u64 v[132:133], v[134:135], 0, v[132:133]
	s_mov_b32 m0, s4
	v_add_u32_e32 v136, 0x8000, v139
	global_load_lds_dwordx4 v[132:133], off
	v_add_u32_e32 v132, v174, v148
	v_ashrrev_i32_e32 v133, 31, v132
	v_lshlrev_b64 v[132:133], 13, v[132:133]
	v_readfirstlane_b32 s4, v136
	v_lshl_add_u64 v[132:133], v[134:135], 0, v[132:133]
	s_mov_b32 m0, s4
	v_add_u32_e32 v131, 0x8000, v131
	global_load_lds_dwordx4 v[132:133], off
	v_add_u32_e32 v132, v173, v148
	v_ashrrev_i32_e32 v133, 31, v132
	v_lshlrev_b64 v[132:133], 13, v[132:133]
	v_readfirstlane_b32 s4, v131
	v_lshl_add_u64 v[132:133], v[134:135], 0, v[132:133]
	s_mov_b32 m0, s4
	s_nop 0
	global_load_lds_dwordx4 v[132:133], off
	s_branch .LBB0_224
